# attention loop: cross-half row max (mov + permlane32_swap + max) moved from every tile into the now-rare rescale block
# baseline (speedup 1.0000x reference)
.Latt_loop:
	s_waitcnt vmcnt(0)
	s_barrier
	ds_read_b128 v[64:67], v173 offset:24576
	ds_read_b128 v[68:71], v173 offset:28672
	s_mov_b32 m0, s44
	ds_read_b128 v[72:75], v171 offset:24576
	global_load_lds_dwordx4 v200, s[40:41]
	s_add_u32 m0, s44, 0x400
	ds_read_b128 v[76:79], v171 offset:28672
	global_load_lds_dwordx4 v190, s[40:41]
	s_mov_b32 m0, s45
	ds_read_b128 v[216:219], v169 offset:24576
	global_load_lds_dwordx4 v192, s[42:43]
	s_add_u32 m0, s45, 0x400
	ds_read_b128 v[220:223], v169 offset:28672
	global_load_lds_dwordx4 v194, s[42:43]
	s_add_u32 m0, s45, 0x800
	ds_read_b128 v[224:227], v167 offset:24576
	global_load_lds_dwordx4 v196, s[42:43]
	s_add_u32 m0, s45, 0xc00
	ds_read_b128 v[228:231], v167 offset:28672
	global_load_lds_dwordx4 v198, s[42:43]
	ds_read_b128 v[232:235], v173 offset:32768
	ds_read_b128 v[236:239], v173 offset:36864
	ds_read_b128 v[240:243], v173 offset:40960
	ds_read_b128 v[244:247], v173 offset:45056
	s_add_u32 s40, s40, 0x18000
	s_addc_u32 s41, s41, 0
	s_add_u32 s42, s42, 0x80
	s_addc_u32 s43, s43, 0
	s_waitcnt lgkmcnt(11)
	v_mfma_f32_32x32x16_bf16 v[112:127], v[64:67], v[140:143], v[96:111]
	ds_read_b128 v[64:67], v171 offset:32768
	s_waitcnt lgkmcnt(11)
	v_mfma_f32_32x32x16_bf16 v[80:95], v[68:71], v[140:143], v[96:111]
	ds_read_b128 v[68:71], v171 offset:36864
	s_waitcnt lgkmcnt(11)
	v_mfma_f32_32x32x16_bf16 v[112:127], v[72:75], v[136:139], v[112:127]
	ds_read_b128 v[72:75], v171 offset:40960
	s_waitcnt lgkmcnt(11)
	v_mfma_f32_32x32x16_bf16 v[80:95], v[76:79], v[136:139], v[80:95]
	ds_read_b128 v[76:79], v171 offset:45056
	s_waitcnt lgkmcnt(11)
	v_mfma_f32_32x32x16_bf16 v[112:127], v[216:219], v[132:135], v[112:127]
	ds_read_b128 v[216:219], v169 offset:32768
	s_waitcnt lgkmcnt(11)
	v_mfma_f32_32x32x16_bf16 v[80:95], v[220:223], v[132:135], v[80:95]
	ds_read_b128 v[220:223], v169 offset:36864
	s_waitcnt lgkmcnt(11)
	v_mfma_f32_32x32x16_bf16 v[112:127], v[224:227], v[128:131], v[112:127]
	ds_read_b128 v[224:227], v169 offset:40960
	s_waitcnt lgkmcnt(11)
	v_mfma_f32_32x32x16_bf16 v[80:95], v[228:231], v[128:131], v[80:95]
	ds_read_b128 v[228:231], v169 offset:45056
	s_nop 7
	s_nop 3
	v_max3_f32 v175, v112, v113, v114
	v_max3_f32 v177, v115, v116, v117
	v_max3_f32 v179, v118, v119, v120
	v_max3_f32 v181, v121, v122, v123
	v_max3_f32 v248, v124, v125, v126
	v_max3_f32 v249, v127, v80, v81
	v_max3_f32 v250, v82, v83, v84
	v_max3_f32 v251, v85, v86, v87
	v_max3_f32 v253, v88, v89, v90
	v_max3_f32 v254, v91, v92, v93
	v_max_f32_e32 v255, v94, v95
	v_max3_f32 v175, v175, v177, v179
	v_max3_f32 v181, v181, v248, v249
	v_max3_f32 v250, v250, v251, v253
	v_max_f32_e32 v254, v254, v255
	v_max3_f32 v175, v175, v181, v250
	v_max_f32_e32 v175, v175, v254
	v_cmp_lt_f32_e32 vcc, 0x41000000, v175
	s_cbranch_vccnz .Latt_resc_a
.Latt_cont_a:
	v_exp_f32_e32 v112, v112
	v_exp_f32_e32 v113, v113
	v_exp_f32_e32 v114, v114
	v_exp_f32_e32 v115, v115
	v_exp_f32_e32 v116, v116
	v_exp_f32_e32 v117, v117
	v_exp_f32_e32 v118, v118
	v_exp_f32_e32 v119, v119
	v_add_f32_e32 v183, v112, v113
	v_add_f32_e32 v183, v183, v114
	v_add_f32_e32 v183, v183, v115
	v_add_f32_e32 v183, v183, v116
	v_add_f32_e32 v183, v183, v117
	v_add_f32_e32 v183, v183, v118
	v_add_f32_e32 v183, v183, v119
	v_cvt_pk_bf16_f32 v112, v112, v113
	v_cvt_pk_bf16_f32 v113, v114, v115
	v_cvt_pk_bf16_f32 v114, v116, v117
	v_cvt_pk_bf16_f32 v115, v118, v119
	v_exp_f32_e32 v120, v120
	v_exp_f32_e32 v121, v121
	s_waitcnt lgkmcnt(8)
	v_mfma_f32_32x32x16_bf16 v[48:63], v[232:235], v[112:115], v[48:63]
	v_exp_f32_e32 v122, v122
	v_exp_f32_e32 v123, v123
	v_exp_f32_e32 v124, v124
	v_mfma_f32_32x32x16_bf16 v[32:47], v[236:239], v[112:115], v[32:47]
	v_exp_f32_e32 v125, v125
	v_exp_f32_e32 v126, v126
	v_exp_f32_e32 v127, v127
	v_mfma_f32_32x32x16_bf16 v[16:31], v[240:243], v[112:115], v[16:31]
	v_add_f32_e32 v185, v120, v121
	v_add_f32_e32 v185, v185, v122
	v_add_f32_e32 v185, v185, v123
	v_add_f32_e32 v185, v185, v124
	v_add_f32_e32 v185, v185, v125
	v_add_f32_e32 v185, v185, v126
	v_mfma_f32_32x32x16_bf16 v[0:15], v[244:247], v[112:115], v[0:15]
	ds_read_b128 v[232:235], v167 offset:32768
	ds_read_b128 v[236:239], v167 offset:36864
	ds_read_b128 v[240:243], v167 offset:40960
	ds_read_b128 v[244:247], v167 offset:45056
	v_add_f32_e32 v185, v185, v127
	v_cvt_pk_bf16_f32 v116, v120, v121
	v_cvt_pk_bf16_f32 v117, v122, v123
	v_cvt_pk_bf16_f32 v118, v124, v125
	v_cvt_pk_bf16_f32 v119, v126, v127
	s_nop 0
	s_waitcnt lgkmcnt(8)
	v_mfma_f32_32x32x16_bf16 v[48:63], v[64:67], v[116:119], v[48:63]
	v_exp_f32_e32 v80, v80
	v_exp_f32_e32 v81, v81
	v_exp_f32_e32 v82, v82
	v_mfma_f32_32x32x16_bf16 v[32:47], v[68:71], v[116:119], v[32:47]
	v_exp_f32_e32 v83, v83
	v_exp_f32_e32 v84, v84
	v_exp_f32_e32 v85, v85
	v_mfma_f32_32x32x16_bf16 v[16:31], v[72:75], v[116:119], v[16:31]
	v_exp_f32_e32 v86, v86
	v_exp_f32_e32 v87, v87
	v_add_f32_e32 v187, v80, v81
	v_add_f32_e32 v187, v187, v82
	v_mfma_f32_32x32x16_bf16 v[0:15], v[76:79], v[116:119], v[0:15]
	v_add_f32_e32 v187, v187, v83
	v_add_f32_e32 v187, v187, v84
	v_add_f32_e32 v187, v187, v85
	v_add_f32_e32 v187, v187, v86
	v_add_f32_e32 v187, v187, v87
	v_cvt_pk_bf16_f32 v80, v80, v81
	v_cvt_pk_bf16_f32 v81, v82, v83
	v_cvt_pk_bf16_f32 v82, v84, v85
	v_cvt_pk_bf16_f32 v83, v86, v87
	s_nop 0
	s_waitcnt lgkmcnt(4)
	v_mfma_f32_32x32x16_bf16 v[48:63], v[216:219], v[80:83], v[48:63]
	v_exp_f32_e32 v88, v88
	v_exp_f32_e32 v89, v89
	v_exp_f32_e32 v90, v90
	v_mfma_f32_32x32x16_bf16 v[32:47], v[220:223], v[80:83], v[32:47]
	v_exp_f32_e32 v91, v91
	v_exp_f32_e32 v92, v92
	v_exp_f32_e32 v93, v93
	v_mfma_f32_32x32x16_bf16 v[16:31], v[224:227], v[80:83], v[16:31]
	v_exp_f32_e32 v94, v94
	v_exp_f32_e32 v95, v95
	v_add_f32_e32 v215, v88, v89
	v_add_f32_e32 v215, v215, v90
	v_mfma_f32_32x32x16_bf16 v[0:15], v[228:231], v[80:83], v[0:15]
	v_add_f32_e32 v215, v215, v91
	v_add_f32_e32 v215, v215, v92
	v_add_f32_e32 v215, v215, v93
	v_add_f32_e32 v215, v215, v94
	v_add_f32_e32 v215, v215, v95
	v_cvt_pk_bf16_f32 v84, v88, v89
	v_cvt_pk_bf16_f32 v85, v90, v91
	v_cvt_pk_bf16_f32 v86, v92, v93
	v_cvt_pk_bf16_f32 v87, v94, v95
	s_nop 0
	s_waitcnt lgkmcnt(0)
	v_mfma_f32_32x32x16_bf16 v[48:63], v[232:235], v[84:87], v[48:63]
	v_add_f32_e32 v183, v183, v185
	v_add_f32_e32 v187, v187, v215
	v_add_f32_e32 v183, v183, v187
	v_mov_b32_e32 v185, v183
	v_mfma_f32_32x32x16_bf16 v[32:47], v[236:239], v[84:87], v[32:47]
	v_mfma_f32_32x32x16_bf16 v[16:31], v[240:243], v[84:87], v[16:31]
	v_mfma_f32_32x32x16_bf16 v[0:15], v[244:247], v[84:87], v[0:15]
	s_nop 0
	s_nop 0
	v_permlane32_swap_b32_e32 v183, v185
	v_add_f32_e32 v183, v183, v185
	v_add_f32_e32 v189, v189, v183
	s_waitcnt vmcnt(0)
	s_barrier
	ds_read_b128 v[64:67], v173 offset:0
	ds_read_b128 v[68:71], v173 offset:4096
	s_add_u32 m0, s44, 0x6000
	ds_read_b128 v[72:75], v171 offset:0
	global_load_lds_dwordx4 v200, s[40:41]
	s_add_u32 m0, s44, 0x6400
	ds_read_b128 v[76:79], v171 offset:4096
	global_load_lds_dwordx4 v190, s[40:41]
	s_add_u32 m0, s45, 0x6000
	ds_read_b128 v[216:219], v169 offset:0
	global_load_lds_dwordx4 v192, s[42:43]
	s_add_u32 m0, s45, 0x6400
	ds_read_b128 v[220:223], v169 offset:4096
	global_load_lds_dwordx4 v194, s[42:43]
	s_add_u32 m0, s45, 0x6800
	ds_read_b128 v[224:227], v167 offset:0
	global_load_lds_dwordx4 v196, s[42:43]
	s_add_u32 m0, s45, 0x6c00
	ds_read_b128 v[228:231], v167 offset:4096
	global_load_lds_dwordx4 v198, s[42:43]
	ds_read_b128 v[232:235], v173 offset:8192
	ds_read_b128 v[236:239], v173 offset:12288
	ds_read_b128 v[240:243], v173 offset:16384
	ds_read_b128 v[244:247], v173 offset:20480
	s_add_u32 s40, s40, 0x18000
	s_addc_u32 s41, s41, 0
	s_add_u32 s42, s42, 0x80
	s_addc_u32 s43, s43, 0
	s_waitcnt lgkmcnt(11)
	v_mfma_f32_32x32x16_bf16 v[112:127], v[64:67], v[140:143], v[96:111]
	ds_read_b128 v[64:67], v171 offset:8192
	s_waitcnt lgkmcnt(11)
	v_mfma_f32_32x32x16_bf16 v[80:95], v[68:71], v[140:143], v[96:111]
	ds_read_b128 v[68:71], v171 offset:12288
	s_waitcnt lgkmcnt(11)
	v_mfma_f32_32x32x16_bf16 v[112:127], v[72:75], v[136:139], v[112:127]
	ds_read_b128 v[72:75], v171 offset:16384
	s_waitcnt lgkmcnt(11)
	v_mfma_f32_32x32x16_bf16 v[80:95], v[76:79], v[136:139], v[80:95]
	ds_read_b128 v[76:79], v171 offset:20480
	s_waitcnt lgkmcnt(11)
	v_mfma_f32_32x32x16_bf16 v[112:127], v[216:219], v[132:135], v[112:127]
	ds_read_b128 v[216:219], v169 offset:8192
	s_waitcnt lgkmcnt(11)
	v_mfma_f32_32x32x16_bf16 v[80:95], v[220:223], v[132:135], v[80:95]
	ds_read_b128 v[220:223], v169 offset:12288
	s_waitcnt lgkmcnt(11)
	v_mfma_f32_32x32x16_bf16 v[112:127], v[224:227], v[128:131], v[112:127]
	ds_read_b128 v[224:227], v169 offset:16384
	s_waitcnt lgkmcnt(11)
	v_mfma_f32_32x32x16_bf16 v[80:95], v[228:231], v[128:131], v[80:95]
	ds_read_b128 v[228:231], v169 offset:20480
	s_nop 7
	s_nop 3
	v_max3_f32 v175, v112, v113, v114
	v_max3_f32 v177, v115, v116, v117
	v_max3_f32 v179, v118, v119, v120
	v_max3_f32 v181, v121, v122, v123
	v_max3_f32 v248, v124, v125, v126
	v_max3_f32 v249, v127, v80, v81
	v_max3_f32 v250, v82, v83, v84
	v_max3_f32 v251, v85, v86, v87
	v_max3_f32 v253, v88, v89, v90
	v_max3_f32 v254, v91, v92, v93
	v_max_f32_e32 v255, v94, v95
	v_max3_f32 v175, v175, v177, v179
	v_max3_f32 v181, v181, v248, v249
	v_max3_f32 v250, v250, v251, v253
	v_max_f32_e32 v254, v254, v255
	v_max3_f32 v175, v175, v181, v250
	v_max_f32_e32 v175, v175, v254
	v_cmp_lt_f32_e32 vcc, 0x41000000, v175
	s_cbranch_vccnz .Latt_resc_b
